# hazard audit: 2 wait states between a 16-byte store and the VALU rewrite of its data registers restored in the P5 epilogue; phase_final row loads issued together
# speedup vs baseline: 1.0602x; 1.0014x over previous
; __device__ __forceinline__ float sigmoidf_(float x) { return __builtin_amdgcn_rcpf(1.0f + __expf(-x)); }
; __device__ __forceinline__ void unpack8(const u32x4 w, float* f) { f[0] = bf_lo(w.x); f[1] = bf_hi(w.x); f[2] = bf_lo(w.y); f[3] = bf_hi(w.y); f[4] = bf_lo(w.z); f[5] = bf_hi(w.z); f[6] = bf_lo(w.w); f[7] = bf_hi(w.w); }
; __device__ __forceinline__ u32x4 pack8(const float* f) { u32x4 w; w.x = cvt_pk_bf16(f[0], f[1]); w.y = cvt_pk_bf16(f[2], f[3]); w.z = cvt_pk_bf16(f[4], f[5]); w.w = cvt_pk_bf16(f[6], f[7]); return w; }
;     __device__ __forceinline__ void operator()(const f32x4 (&acc)[2][2][4][2], const Unit& u, int wr, int wc, int fr, int fq) const { if (u.kind == 0) e0(acc, u, wr, wc, fr, fq); else e1(acc, u, wr, wc, fr, fq); }
;     __device__ __forceinline__ void operator()(const f32x4 (&acc)[2][2][4][2], const Unit& u, int wr, int wc, int fr, int fq) const {
;         const int row0 = u.pm * BM + wr * 64 + fr, col0 = u.pn * BM + wc * 32 + 8 * fq;
; #pragma unroll
;         for (int ai = 0; ai < 2; ++ai)
; #pragma unroll
;             for (int m = 0; m < 4; ++m) { const int row = row0 + ai * HALF + m * 16;
; #pragma unroll
;                 for (int bj = 0; bj < 2; ++bj) { const int col = col0 + bj * HALF;
;                     float gf[8], r[8]; unpack8(*(const u32x4*)(gr + (size_t)row * NPROJ + col), gf);
;                     const f32x4 v0 = acc[ai][bj][m][0], v1 = acc[ai][bj][m][1];
; #pragma unroll
;                     for (int j = 0; j < 4; ++j) { r[j] = v0[j] * sigmoidf_(gf[j]); r[4 + j] = v1[j] * sigmoidf_(gf[4 + j]); }
;                     *(u32x4*)(O + (size_t)row * D + col) = pack8(r); } }
;     }
.LBB0_548:
	v_mov_b64_e32 v[132:133], s[40:41]
	v_mad_i64_i32 v[134:135], s[10:11], v166, s18, v[132:133]
	v_lshlrev_b64 v[2:3], 1, v[164:165]
	v_ashrrev_i32_e32 v167, 31, v166
	v_lshl_add_u64 v[134:135], v[134:135], 0, v[2:3]
	v_lshlrev_b64 v[136:137], 11, v[166:167]
	v_mad_i64_i32 v[230:231], s[98:99], v166, s18, v[132:133]
	v_lshl_add_u64 v[230:231], v[230:231], 0, v[2:3]
	global_load_dwordx4 v[168:171], v[230:231], off
	global_load_dwordx4 v[190:193], v[230:231], off offset:256
	v_mad_i64_i32 v[230:231], s[98:99], v162, s18, v[132:133]
	v_lshl_add_u64 v[230:231], v[230:231], 0, v[2:3]
	global_load_dwordx4 v[194:197], v[230:231], off
	global_load_dwordx4 v[198:201], v[230:231], off offset:256
	v_mad_i64_i32 v[230:231], s[98:99], v160, s18, v[132:133]
	v_lshl_add_u64 v[230:231], v[230:231], 0, v[2:3]
	global_load_dwordx4 v[202:205], v[230:231], off
	global_load_dwordx4 v[206:209], v[230:231], off offset:256
	v_mad_i64_i32 v[230:231], s[98:99], v158, s18, v[132:133]
	v_lshl_add_u64 v[230:231], v[230:231], 0, v[2:3]
	global_load_dwordx4 v[210:213], v[230:231], off
	global_load_dwordx4 v[214:217], v[230:231], off offset:256
	v_mad_i64_i32 v[230:231], s[98:99], v156, s18, v[132:133]
	v_lshl_add_u64 v[230:231], v[230:231], 0, v[2:3]
	global_load_dwordx4 v[218:221], v[230:231], off
	global_load_dwordx4 v[222:225], v[230:231], off offset:256
	v_mad_i64_i32 v[230:231], s[98:99], v154, s18, v[132:133]
	v_lshl_add_u64 v[230:231], v[230:231], 0, v[2:3]
	global_load_dwordx4 v[226:229], v[230:231], off
	global_load_dwordx4 v[236:239], v[230:231], off offset:256
	s_waitcnt vmcnt(11)
	s_nop 0
	v_mov_b64_e32 v[164:165], v[168:169]
	v_mov_b64_e32 v[166:167], v[170:171]
	s_and_b64 vcc, exec, s[4:5]
	s_mov_b64 s[28:29], s[0:1]
	s_mov_b64 s[42:43], s[6:7]
	v_lshlrev_b32_e32 v0, 16, v164
	v_mul_f32_e32 v0, 0xbfb8aa3b, v0
	v_exp_f32_e32 v0, v0
	v_lshlrev_b32_e32 v157, 16, v166
	v_and_b32_e32 v151, 0xffff0000, v164
	v_and_b32_e32 v159, 0xffff0000, v166
	v_add_f32_e32 v0, 1.0, v0
	v_rcp_f32_e32 v164, v0
	v_mul_f32_e32 v0, 0xbfb8aa3b, v157
	v_exp_f32_e32 v0, v0
	v_lshlrev_b32_e32 v153, 16, v165
	v_and_b32_e32 v155, 0xffff0000, v165
	v_lshlrev_b32_e32 v161, 16, v167
	v_add_f32_e32 v0, 1.0, v0
	v_rcp_f32_e32 v166, v0
	v_mul_f32_e32 v0, 0xbfb8aa3b, v151
	v_exp_f32_e32 v0, v0
	v_and_b32_e32 v163, 0xffff0000, v167
	v_ashrrev_i32_e32 v157, 31, v156
	v_ashrrev_i32_e32 v151, 31, v150
	v_add_f32_e32 v0, 1.0, v0
	v_rcp_f32_e32 v165, v0
	v_mul_f32_e32 v0, 0xbfb8aa3b, v159
	v_exp_f32_e32 v0, v0
	v_ashrrev_i32_e32 v159, 31, v158
	v_pk_mul_f32 v[128:129], v[128:129], v[164:165]
	v_add_f32_e32 v0, 1.0, v0
	v_rcp_f32_e32 v167, v0
	v_mul_f32_e32 v0, 0xbfb8aa3b, v153
	v_exp_f32_e32 v0, v0
	v_ashrrev_i32_e32 v153, 31, v152
	v_pk_mul_f32 v[164:165], v[124:125], v[166:167]
	v_add_f32_e32 v0, 1.0, v0
	v_rcp_f32_e32 v124, v0
	v_mul_f32_e32 v0, 0xbfb8aa3b, v161
	v_exp_f32_e32 v0, v0
	v_ashrrev_i32_e32 v161, 31, v160
	v_add_f32_e32 v0, 1.0, v0
	v_rcp_f32_e32 v166, v0
	v_mul_f32_e32 v0, 0xbfb8aa3b, v155
	v_exp_f32_e32 v0, v0
	v_ashrrev_i32_e32 v155, 31, v154
	v_add_f32_e32 v0, 1.0, v0
	v_rcp_f32_e32 v125, v0
	v_mul_f32_e32 v0, 0xbfb8aa3b, v163
	v_exp_f32_e32 v0, v0
	v_ashrrev_i32_e32 v163, 31, v162
	v_pk_mul_f32 v[130:131], v[130:131], v[124:125]
	v_cvt_pk_bf16_f32 v124, v128, v129
	v_add_f32_e32 v0, 1.0, v0
	v_rcp_f32_e32 v167, v0
	v_lshl_add_u64 v[128:129], s[94:95], 0, v[136:137]
	v_cvt_pk_bf16_f32 v125, v130, v131
	v_lshl_add_u64 v[128:129], v[128:129], 0, v[2:3]
	v_pk_mul_f32 v[166:167], v[126:127], v[166:167]
	v_cvt_pk_bf16_f32 v126, v164, v165
	v_cvt_pk_bf16_f32 v127, v166, v167
	global_store_dwordx4 v[128:129], v[124:127], off
	s_waitcnt vmcnt(10)
	s_nop 0
	v_mov_b64_e32 v[124:125], v[190:191]
	v_mov_b64_e32 v[126:127], v[192:193]
	v_mad_i64_i32 v[230:231], s[98:99], v152, s18, v[132:133]
	v_lshl_add_u64 v[230:231], v[230:231], 0, v[2:3]
	global_load_dwordx4 v[168:171], v[230:231], off
	global_load_dwordx4 v[190:193], v[230:231], off offset:256
	v_lshlrev_b32_e32 v0, 16, v124
	v_mul_f32_e32 v0, 0xbfb8aa3b, v0
	v_exp_f32_e32 v0, v0
	v_lshlrev_b32_e32 v131, 16, v125
	v_and_b32_e32 v134, 0xffff0000, v125
	v_lshlrev_b32_e32 v125, 16, v126
	v_add_f32_e32 v0, 1.0, v0
	v_and_b32_e32 v130, 0xffff0000, v124
	v_rcp_f32_e32 v124, v0
	v_mul_f32_e32 v0, 0xbfb8aa3b, v125
	v_exp_f32_e32 v0, v0
	v_and_b32_e32 v135, 0xffff0000, v126
	v_lshlrev_b32_e32 v136, 16, v127
	v_and_b32_e32 v137, 0xffff0000, v127
	v_add_f32_e32 v0, 1.0, v0
	v_rcp_f32_e32 v126, v0
	v_mul_f32_e32 v0, 0xbfb8aa3b, v130
	v_exp_f32_e32 v0, v0
	s_nop 0
	v_add_f32_e32 v0, 1.0, v0
	v_rcp_f32_e32 v125, v0
	v_mul_f32_e32 v0, 0xbfb8aa3b, v135
	v_exp_f32_e32 v0, v0
	v_pk_mul_f32 v[120:121], v[120:121], v[124:125]
	v_add_f32_e32 v0, 1.0, v0
	v_rcp_f32_e32 v127, v0
	v_mul_f32_e32 v0, 0xbfb8aa3b, v131
	v_exp_f32_e32 v0, v0
	v_pk_mul_f32 v[124:125], v[116:117], v[126:127]
	v_add_f32_e32 v0, 1.0, v0
	v_rcp_f32_e32 v116, v0
	v_mul_f32_e32 v0, 0xbfb8aa3b, v136
	v_exp_f32_e32 v0, v0
	s_nop 0
	v_add_f32_e32 v0, 1.0, v0
	v_rcp_f32_e32 v126, v0
	v_mul_f32_e32 v0, 0xbfb8aa3b, v134
	v_exp_f32_e32 v0, v0
	s_nop 0
	v_add_f32_e32 v0, 1.0, v0
	v_rcp_f32_e32 v117, v0
	v_mul_f32_e32 v0, 0xbfb8aa3b, v137
	v_exp_f32_e32 v0, v0
	v_pk_mul_f32 v[122:123], v[122:123], v[116:117]
	v_cvt_pk_bf16_f32 v116, v120, v121
	v_add_f32_e32 v0, 1.0, v0
	v_rcp_f32_e32 v127, v0
	v_cvt_pk_bf16_f32 v117, v122, v123
	v_pk_mul_f32 v[126:127], v[118:119], v[126:127]
	v_cvt_pk_bf16_f32 v118, v124, v125
	v_cvt_pk_bf16_f32 v119, v126, v127
	global_store_dwordx4 v[128:129], v[116:119], off offset:256
	s_nop 1
	v_mad_i64_i32 v[118:119], s[10:11], v162, s18, v[132:133]
	v_lshl_add_u64 v[118:119], v[118:119], 0, v[2:3]
	s_waitcnt vmcnt(11)
; __device__ __forceinline__ float sigmoidf_(float x) { return __builtin_amdgcn_rcpf(1.0f + __expf(-x)); }
; __device__ __forceinline__ void unpack8(const u32x4 w, float* f) { f[0] = bf_lo(w.x); f[1] = bf_hi(w.x); f[2] = bf_lo(w.y); f[3] = bf_hi(w.y); f[4] = bf_lo(w.z); f[5] = bf_hi(w.z); f[6] = bf_lo(w.w); f[7] = bf_hi(w.w); }
; __device__ __forceinline__ u32x4 pack8(const float* f) { u32x4 w; w.x = cvt_pk_bf16(f[0], f[1]); w.y = cvt_pk_bf16(f[2], f[3]); w.z = cvt_pk_bf16(f[4], f[5]); w.w = cvt_pk_bf16(f[6], f[7]); return w; }
;     __device__ __forceinline__ void operator()(const f32x4 (&acc)[2][2][4][2], const Unit& u, int wr, int wc, int fr, int fq) const { if (u.kind == 0) e0(acc, u, wr, wc, fr, fq); else e1(acc, u, wr, wc, fr, fq); }
;     __device__ __forceinline__ void operator()(const f32x4 (&acc)[2][2][4][2], const Unit& u, int wr, int wc, int fr, int fq) const {
;         const int row0 = u.pm * BM + wr * 64 + fr, col0 = u.pn * BM + wc * 32 + 8 * fq;
; #pragma unroll
;         for (int ai = 0; ai < 2; ++ai)
; #pragma unroll
;             for (int m = 0; m < 4; ++m) { const int row = row0 + ai * HALF + m * 16;
; #pragma unroll
;                 for (int bj = 0; bj < 2; ++bj) { const int col = col0 + bj * HALF;
;                     float gf[8], r[8]; unpack8(*(const u32x4*)(gr + (size_t)row * NPROJ + col), gf);
;                     const f32x4 v0 = acc[ai][bj][m][0], v1 = acc[ai][bj][m][1];
; #pragma unroll
;                     for (int j = 0; j < 4; ++j) { r[j] = v0[j] * sigmoidf_(gf[j]); r[4 + j] = v1[j] * sigmoidf_(gf[4 + j]); }
;                     *(u32x4*)(O + (size_t)row * D + col) = pack8(r); } }
;     }
	s_nop 0
	v_mov_b64_e32 v[120:121], v[194:195]
	v_mov_b64_e32 v[122:123], v[196:197]
	v_lshlrev_b64 v[116:117], 11, v[162:163]
	v_lshlrev_b32_e32 v0, 16, v120
	v_mul_f32_e32 v0, 0xbfb8aa3b, v0
	v_exp_f32_e32 v0, v0
	v_lshlrev_b32_e32 v125, 16, v121
	v_and_b32_e32 v126, 0xffff0000, v121
	v_lshlrev_b32_e32 v121, 16, v122
	v_add_f32_e32 v0, 1.0, v0
	v_and_b32_e32 v124, 0xffff0000, v120
	v_rcp_f32_e32 v120, v0
	v_mul_f32_e32 v0, 0xbfb8aa3b, v121
	v_exp_f32_e32 v0, v0
	v_and_b32_e32 v127, 0xffff0000, v122
	v_lshlrev_b32_e32 v128, 16, v123
	v_and_b32_e32 v129, 0xffff0000, v123
	v_add_f32_e32 v0, 1.0, v0
	v_rcp_f32_e32 v122, v0
	v_mul_f32_e32 v0, 0xbfb8aa3b, v124
	v_exp_f32_e32 v0, v0
	s_nop 0
	v_add_f32_e32 v0, 1.0, v0
	v_rcp_f32_e32 v121, v0
	v_mul_f32_e32 v0, 0xbfb8aa3b, v127
	v_exp_f32_e32 v0, v0
	v_pk_mul_f32 v[112:113], v[112:113], v[120:121]
	v_add_f32_e32 v0, 1.0, v0
	v_rcp_f32_e32 v123, v0
	v_mul_f32_e32 v0, 0xbfb8aa3b, v125
	v_exp_f32_e32 v0, v0
	v_pk_mul_f32 v[120:121], v[108:109], v[122:123]
	v_add_f32_e32 v0, 1.0, v0
	v_rcp_f32_e32 v108, v0
	v_mul_f32_e32 v0, 0xbfb8aa3b, v128
	v_exp_f32_e32 v0, v0
	s_nop 0
	v_add_f32_e32 v0, 1.0, v0
	v_rcp_f32_e32 v122, v0
	v_mul_f32_e32 v0, 0xbfb8aa3b, v126
	v_exp_f32_e32 v0, v0
	s_nop 0
	v_add_f32_e32 v0, 1.0, v0
	v_rcp_f32_e32 v109, v0
	v_mul_f32_e32 v0, 0xbfb8aa3b, v129
	v_exp_f32_e32 v0, v0
	v_pk_mul_f32 v[114:115], v[114:115], v[108:109]
	v_cvt_pk_bf16_f32 v108, v112, v113
	v_add_f32_e32 v0, 1.0, v0
	v_rcp_f32_e32 v123, v0
	v_lshl_add_u64 v[112:113], s[94:95], 0, v[116:117]
	v_cvt_pk_bf16_f32 v109, v114, v115
	v_lshl_add_u64 v[112:113], v[112:113], 0, v[2:3]
	v_pk_mul_f32 v[122:123], v[110:111], v[122:123]
	v_cvt_pk_bf16_f32 v110, v120, v121
	v_cvt_pk_bf16_f32 v111, v122, v123
	global_store_dwordx4 v[112:113], v[108:111], off
	s_waitcnt vmcnt(10)
	s_nop 0
	v_mov_b64_e32 v[108:109], v[198:199]
	v_mov_b64_e32 v[110:111], v[200:201]
	v_mad_i64_i32 v[230:231], s[98:99], v150, s18, v[132:133]
	v_lshl_add_u64 v[230:231], v[230:231], 0, v[2:3]
	global_load_dwordx4 v[194:197], v[230:231], off
	global_load_dwordx4 v[198:201], v[230:231], off offset:256
	v_lshlrev_b32_e32 v0, 16, v108
	v_mul_f32_e32 v0, 0xbfb8aa3b, v0
	v_exp_f32_e32 v0, v0
	v_lshlrev_b32_e32 v115, 16, v109
	v_and_b32_e32 v116, 0xffff0000, v109
	v_lshlrev_b32_e32 v109, 16, v110
	v_add_f32_e32 v0, 1.0, v0
	v_and_b32_e32 v114, 0xffff0000, v108
	v_rcp_f32_e32 v108, v0
	v_mul_f32_e32 v0, 0xbfb8aa3b, v109
	v_exp_f32_e32 v0, v0
	v_and_b32_e32 v117, 0xffff0000, v110
	v_lshlrev_b32_e32 v118, 16, v111
	v_and_b32_e32 v119, 0xffff0000, v111
	v_add_f32_e32 v0, 1.0, v0
	v_rcp_f32_e32 v110, v0
	v_mul_f32_e32 v0, 0xbfb8aa3b, v114
	v_exp_f32_e32 v0, v0
	s_nop 0
	v_add_f32_e32 v0, 1.0, v0
	v_rcp_f32_e32 v109, v0
	v_mul_f32_e32 v0, 0xbfb8aa3b, v117
	v_exp_f32_e32 v0, v0
	v_pk_mul_f32 v[104:105], v[104:105], v[108:109]
	v_add_f32_e32 v0, 1.0, v0
	v_rcp_f32_e32 v111, v0
	v_mul_f32_e32 v0, 0xbfb8aa3b, v115
	v_exp_f32_e32 v0, v0
	v_pk_mul_f32 v[108:109], v[100:101], v[110:111]
	v_add_f32_e32 v0, 1.0, v0
	v_rcp_f32_e32 v100, v0
	v_mul_f32_e32 v0, 0xbfb8aa3b, v118
	v_exp_f32_e32 v0, v0
	s_nop 0
	v_add_f32_e32 v0, 1.0, v0
	v_rcp_f32_e32 v110, v0
	v_mul_f32_e32 v0, 0xbfb8aa3b, v116
	v_exp_f32_e32 v0, v0
	s_nop 0
	v_add_f32_e32 v0, 1.0, v0
	v_rcp_f32_e32 v101, v0
	v_mul_f32_e32 v0, 0xbfb8aa3b, v119
	v_exp_f32_e32 v0, v0
	v_pk_mul_f32 v[106:107], v[106:107], v[100:101]
	v_cvt_pk_bf16_f32 v100, v104, v105
	v_add_f32_e32 v0, 1.0, v0
	v_rcp_f32_e32 v111, v0
	v_cvt_pk_bf16_f32 v101, v106, v107
	v_pk_mul_f32 v[110:111], v[102:103], v[110:111]
	v_cvt_pk_bf16_f32 v102, v108, v109
	v_cvt_pk_bf16_f32 v103, v110, v111
	global_store_dwordx4 v[112:113], v[100:103], off offset:256
	s_nop 1
	v_mad_i64_i32 v[102:103], s[10:11], v160, s18, v[132:133]
	v_lshl_add_u64 v[102:103], v[102:103], 0, v[2:3]
	s_waitcnt vmcnt(11)
	s_nop 0
	v_mov_b64_e32 v[104:105], v[202:203]
	v_mov_b64_e32 v[106:107], v[204:205]
	v_lshlrev_b64 v[100:101], 11, v[160:161]
	v_lshlrev_b32_e32 v0, 16, v104
	v_mul_f32_e32 v0, 0xbfb8aa3b, v0
	v_exp_f32_e32 v0, v0
	v_lshlrev_b32_e32 v109, 16, v105
	v_and_b32_e32 v110, 0xffff0000, v105
	v_lshlrev_b32_e32 v105, 16, v106
	v_add_f32_e32 v0, 1.0, v0
	v_and_b32_e32 v108, 0xffff0000, v104
	v_rcp_f32_e32 v104, v0
	v_mul_f32_e32 v0, 0xbfb8aa3b, v105
	v_exp_f32_e32 v0, v0
	v_and_b32_e32 v111, 0xffff0000, v106
	v_lshlrev_b32_e32 v112, 16, v107
	v_and_b32_e32 v113, 0xffff0000, v107
	v_add_f32_e32 v0, 1.0, v0
	v_rcp_f32_e32 v106, v0
	v_mul_f32_e32 v0, 0xbfb8aa3b, v108
	v_exp_f32_e32 v0, v0
	s_nop 0
	v_add_f32_e32 v0, 1.0, v0
	v_rcp_f32_e32 v105, v0
	v_mul_f32_e32 v0, 0xbfb8aa3b, v111
	v_exp_f32_e32 v0, v0
	v_pk_mul_f32 v[96:97], v[96:97], v[104:105]
	v_add_f32_e32 v0, 1.0, v0
	v_rcp_f32_e32 v107, v0
	v_mul_f32_e32 v0, 0xbfb8aa3b, v109
	v_exp_f32_e32 v0, v0
	v_pk_mul_f32 v[104:105], v[92:93], v[106:107]
	v_add_f32_e32 v0, 1.0, v0
	v_rcp_f32_e32 v92, v0
	v_mul_f32_e32 v0, 0xbfb8aa3b, v112
	v_exp_f32_e32 v0, v0
	s_nop 0
	v_add_f32_e32 v0, 1.0, v0
	v_rcp_f32_e32 v106, v0
	v_mul_f32_e32 v0, 0xbfb8aa3b, v110
	v_exp_f32_e32 v0, v0
	s_nop 0
	v_add_f32_e32 v0, 1.0, v0
	v_rcp_f32_e32 v93, v0
	v_mul_f32_e32 v0, 0xbfb8aa3b, v113
	v_exp_f32_e32 v0, v0
	v_pk_mul_f32 v[98:99], v[98:99], v[92:93]
	v_cvt_pk_bf16_f32 v92, v96, v97
	v_add_f32_e32 v0, 1.0, v0
	v_rcp_f32_e32 v107, v0
	v_lshl_add_u64 v[96:97], s[94:95], 0, v[100:101]
	v_cvt_pk_bf16_f32 v93, v98, v99
	v_lshl_add_u64 v[96:97], v[96:97], 0, v[2:3]
	v_pk_mul_f32 v[106:107], v[94:95], v[106:107]
	v_cvt_pk_bf16_f32 v94, v104, v105
	v_cvt_pk_bf16_f32 v95, v106, v107
	global_store_dwordx4 v[96:97], v[92:95], off
	s_waitcnt vmcnt(10)
; __device__ __forceinline__ float sigmoidf_(float x) { return __builtin_amdgcn_rcpf(1.0f + __expf(-x)); }
; __device__ __forceinline__ void unpack8(const u32x4 w, float* f) { f[0] = bf_lo(w.x); f[1] = bf_hi(w.x); f[2] = bf_lo(w.y); f[3] = bf_hi(w.y); f[4] = bf_lo(w.z); f[5] = bf_hi(w.z); f[6] = bf_lo(w.w); f[7] = bf_hi(w.w); }
; __device__ __forceinline__ u32x4 pack8(const float* f) { u32x4 w; w.x = cvt_pk_bf16(f[0], f[1]); w.y = cvt_pk_bf16(f[2], f[3]); w.z = cvt_pk_bf16(f[4], f[5]); w.w = cvt_pk_bf16(f[6], f[7]); return w; }
;     __device__ __forceinline__ void operator()(const f32x4 (&acc)[2][2][4][2], const Unit& u, int wr, int wc, int fr, int fq) const { if (u.kind == 0) e0(acc, u, wr, wc, fr, fq); else e1(acc, u, wr, wc, fr, fq); }
;     __device__ __forceinline__ void operator()(const f32x4 (&acc)[2][2][4][2], const Unit& u, int wr, int wc, int fr, int fq) const {
;         const int row0 = u.pm * BM + wr * 64 + fr, col0 = u.pn * BM + wc * 32 + 8 * fq;
; #pragma unroll
;         for (int ai = 0; ai < 2; ++ai)
; #pragma unroll
;             for (int m = 0; m < 4; ++m) { const int row = row0 + ai * HALF + m * 16;
; #pragma unroll
;                 for (int bj = 0; bj < 2; ++bj) { const int col = col0 + bj * HALF;
;                     float gf[8], r[8]; unpack8(*(const u32x4*)(gr + (size_t)row * NPROJ + col), gf);
;                     const f32x4 v0 = acc[ai][bj][m][0], v1 = acc[ai][bj][m][1];
; #pragma unroll
;                     for (int j = 0; j < 4; ++j) { r[j] = v0[j] * sigmoidf_(gf[j]); r[4 + j] = v1[j] * sigmoidf_(gf[4 + j]); }
;                     *(u32x4*)(O + (size_t)row * D + col) = pack8(r); } }
;     }
	s_nop 0
	v_mov_b64_e32 v[92:93], v[206:207]
	v_mov_b64_e32 v[94:95], v[208:209]
	v_lshlrev_b32_e32 v0, 16, v92
	v_mul_f32_e32 v0, 0xbfb8aa3b, v0
	v_exp_f32_e32 v0, v0
	v_lshlrev_b32_e32 v99, 16, v93
	v_and_b32_e32 v100, 0xffff0000, v93
	v_lshlrev_b32_e32 v93, 16, v94
	v_add_f32_e32 v0, 1.0, v0
	v_and_b32_e32 v98, 0xffff0000, v92
	v_rcp_f32_e32 v92, v0
	v_mul_f32_e32 v0, 0xbfb8aa3b, v93
	v_exp_f32_e32 v0, v0
	v_and_b32_e32 v101, 0xffff0000, v94
	v_lshlrev_b32_e32 v102, 16, v95
	v_and_b32_e32 v103, 0xffff0000, v95
	v_add_f32_e32 v0, 1.0, v0
	v_rcp_f32_e32 v94, v0
	v_mul_f32_e32 v0, 0xbfb8aa3b, v98
	v_exp_f32_e32 v0, v0
	s_nop 0
	v_add_f32_e32 v0, 1.0, v0
	v_rcp_f32_e32 v93, v0
	v_mul_f32_e32 v0, 0xbfb8aa3b, v101
	v_exp_f32_e32 v0, v0
	v_pk_mul_f32 v[88:89], v[88:89], v[92:93]
	v_add_f32_e32 v0, 1.0, v0
	v_rcp_f32_e32 v95, v0
	v_mul_f32_e32 v0, 0xbfb8aa3b, v99
	v_exp_f32_e32 v0, v0
	v_pk_mul_f32 v[92:93], v[84:85], v[94:95]
	v_add_f32_e32 v0, 1.0, v0
	v_rcp_f32_e32 v84, v0
	v_mul_f32_e32 v0, 0xbfb8aa3b, v102
	v_exp_f32_e32 v0, v0
	s_nop 0
	v_add_f32_e32 v0, 1.0, v0
	v_rcp_f32_e32 v94, v0
	v_mul_f32_e32 v0, 0xbfb8aa3b, v100
	v_exp_f32_e32 v0, v0
	s_nop 0
	v_add_f32_e32 v0, 1.0, v0
	v_rcp_f32_e32 v85, v0
	v_mul_f32_e32 v0, 0xbfb8aa3b, v103
	v_exp_f32_e32 v0, v0
	v_pk_mul_f32 v[90:91], v[90:91], v[84:85]
	v_cvt_pk_bf16_f32 v84, v88, v89
	v_add_f32_e32 v0, 1.0, v0
	v_rcp_f32_e32 v95, v0
	v_cvt_pk_bf16_f32 v85, v90, v91
	v_pk_mul_f32 v[94:95], v[86:87], v[94:95]
	v_cvt_pk_bf16_f32 v86, v92, v93
	v_cvt_pk_bf16_f32 v87, v94, v95
	global_store_dwordx4 v[96:97], v[84:87], off offset:256
	s_nop 1
	v_mad_i64_i32 v[86:87], s[10:11], v158, s18, v[132:133]
	v_lshl_add_u64 v[86:87], v[86:87], 0, v[2:3]
	s_waitcnt vmcnt(9)
	s_nop 0
	v_mov_b64_e32 v[88:89], v[210:211]
	v_mov_b64_e32 v[90:91], v[212:213]
	v_lshlrev_b64 v[84:85], 11, v[158:159]
	v_lshlrev_b32_e32 v0, 16, v88
	v_mul_f32_e32 v0, 0xbfb8aa3b, v0
	v_exp_f32_e32 v0, v0
	v_lshlrev_b32_e32 v93, 16, v89
	v_and_b32_e32 v94, 0xffff0000, v89
	v_lshlrev_b32_e32 v89, 16, v90
	v_add_f32_e32 v0, 1.0, v0
	v_and_b32_e32 v92, 0xffff0000, v88
	v_rcp_f32_e32 v88, v0
	v_mul_f32_e32 v0, 0xbfb8aa3b, v89
	v_exp_f32_e32 v0, v0
	v_and_b32_e32 v95, 0xffff0000, v90
	v_lshlrev_b32_e32 v96, 16, v91
	v_and_b32_e32 v97, 0xffff0000, v91
	v_add_f32_e32 v0, 1.0, v0
	v_rcp_f32_e32 v90, v0
	v_mul_f32_e32 v0, 0xbfb8aa3b, v92
	v_exp_f32_e32 v0, v0
	s_nop 0
	v_add_f32_e32 v0, 1.0, v0
	v_rcp_f32_e32 v89, v0
	v_mul_f32_e32 v0, 0xbfb8aa3b, v95
	v_exp_f32_e32 v0, v0
	v_pk_mul_f32 v[80:81], v[80:81], v[88:89]
	v_add_f32_e32 v0, 1.0, v0
	v_rcp_f32_e32 v91, v0
	v_mul_f32_e32 v0, 0xbfb8aa3b, v93
	v_exp_f32_e32 v0, v0
	v_pk_mul_f32 v[88:89], v[76:77], v[90:91]
	v_add_f32_e32 v0, 1.0, v0
	v_rcp_f32_e32 v76, v0
	v_mul_f32_e32 v0, 0xbfb8aa3b, v96
	v_exp_f32_e32 v0, v0
	s_nop 0
	v_add_f32_e32 v0, 1.0, v0
	v_rcp_f32_e32 v90, v0
	v_mul_f32_e32 v0, 0xbfb8aa3b, v94
	v_exp_f32_e32 v0, v0
	s_nop 0
	v_add_f32_e32 v0, 1.0, v0
	v_rcp_f32_e32 v77, v0
	v_mul_f32_e32 v0, 0xbfb8aa3b, v97
	v_exp_f32_e32 v0, v0
	v_pk_mul_f32 v[82:83], v[82:83], v[76:77]
	v_cvt_pk_bf16_f32 v76, v80, v81
	v_add_f32_e32 v0, 1.0, v0
	v_rcp_f32_e32 v91, v0
	v_lshl_add_u64 v[80:81], s[94:95], 0, v[84:85]
	v_cvt_pk_bf16_f32 v77, v82, v83
	v_lshl_add_u64 v[80:81], v[80:81], 0, v[2:3]
	v_pk_mul_f32 v[90:91], v[78:79], v[90:91]
	v_cvt_pk_bf16_f32 v78, v88, v89
	v_cvt_pk_bf16_f32 v79, v90, v91
	global_store_dwordx4 v[80:81], v[76:79], off
	s_waitcnt vmcnt(8)
	s_nop 0
	v_mov_b64_e32 v[76:77], v[214:215]
	v_mov_b64_e32 v[78:79], v[216:217]
	v_lshlrev_b32_e32 v0, 16, v76
	v_mul_f32_e32 v0, 0xbfb8aa3b, v0
	v_exp_f32_e32 v0, v0
	v_lshlrev_b32_e32 v83, 16, v77
	v_and_b32_e32 v84, 0xffff0000, v77
	v_lshlrev_b32_e32 v77, 16, v78
	v_add_f32_e32 v0, 1.0, v0
	v_and_b32_e32 v82, 0xffff0000, v76
	v_rcp_f32_e32 v76, v0
	v_mul_f32_e32 v0, 0xbfb8aa3b, v77
	v_exp_f32_e32 v0, v0
	v_and_b32_e32 v85, 0xffff0000, v78
	v_lshlrev_b32_e32 v86, 16, v79
	v_and_b32_e32 v87, 0xffff0000, v79
	v_add_f32_e32 v0, 1.0, v0
	v_rcp_f32_e32 v78, v0
	v_mul_f32_e32 v0, 0xbfb8aa3b, v82
	v_exp_f32_e32 v0, v0
	s_nop 0
	v_add_f32_e32 v0, 1.0, v0
	v_rcp_f32_e32 v77, v0
	v_mul_f32_e32 v0, 0xbfb8aa3b, v85
	v_exp_f32_e32 v0, v0
	v_pk_mul_f32 v[72:73], v[72:73], v[76:77]
	v_add_f32_e32 v0, 1.0, v0
	v_rcp_f32_e32 v79, v0
	v_mul_f32_e32 v0, 0xbfb8aa3b, v83
	v_exp_f32_e32 v0, v0
	v_pk_mul_f32 v[76:77], v[68:69], v[78:79]
	v_add_f32_e32 v0, 1.0, v0
	v_rcp_f32_e32 v68, v0
	v_mul_f32_e32 v0, 0xbfb8aa3b, v86
	v_exp_f32_e32 v0, v0
	s_nop 0
	v_add_f32_e32 v0, 1.0, v0
	v_rcp_f32_e32 v78, v0
	v_mul_f32_e32 v0, 0xbfb8aa3b, v84
	v_exp_f32_e32 v0, v0
	s_nop 0
	v_add_f32_e32 v0, 1.0, v0
	v_rcp_f32_e32 v69, v0
	v_mul_f32_e32 v0, 0xbfb8aa3b, v87
	v_exp_f32_e32 v0, v0
	v_pk_mul_f32 v[74:75], v[74:75], v[68:69]
	v_cvt_pk_bf16_f32 v68, v72, v73
	v_add_f32_e32 v0, 1.0, v0
	v_rcp_f32_e32 v79, v0
	v_cvt_pk_bf16_f32 v69, v74, v75
	v_pk_mul_f32 v[78:79], v[70:71], v[78:79]
	v_cvt_pk_bf16_f32 v70, v76, v77
	v_cvt_pk_bf16_f32 v71, v78, v79
	global_store_dwordx4 v[80:81], v[68:71], off offset:256
	s_nop 1
	v_mad_i64_i32 v[70:71], s[10:11], v156, s18, v[132:133]
	v_lshl_add_u64 v[70:71], v[70:71], 0, v[2:3]
	s_waitcnt vmcnt(7)
; __device__ __forceinline__ float sigmoidf_(float x) { return __builtin_amdgcn_rcpf(1.0f + __expf(-x)); }
; __device__ __forceinline__ void unpack8(const u32x4 w, float* f) { f[0] = bf_lo(w.x); f[1] = bf_hi(w.x); f[2] = bf_lo(w.y); f[3] = bf_hi(w.y); f[4] = bf_lo(w.z); f[5] = bf_hi(w.z); f[6] = bf_lo(w.w); f[7] = bf_hi(w.w); }
; __device__ __forceinline__ u32x4 pack8(const float* f) { u32x4 w; w.x = cvt_pk_bf16(f[0], f[1]); w.y = cvt_pk_bf16(f[2], f[3]); w.z = cvt_pk_bf16(f[4], f[5]); w.w = cvt_pk_bf16(f[6], f[7]); return w; }
;     __device__ __forceinline__ void operator()(const f32x4 (&acc)[2][2][4][2], const Unit& u, int wr, int wc, int fr, int fq) const { if (u.kind == 0) e0(acc, u, wr, wc, fr, fq); else e1(acc, u, wr, wc, fr, fq); }
;     __device__ __forceinline__ void operator()(const f32x4 (&acc)[2][2][4][2], const Unit& u, int wr, int wc, int fr, int fq) const {
;         const int row0 = u.pm * BM + wr * 64 + fr, col0 = u.pn * BM + wc * 32 + 8 * fq;
; #pragma unroll
;         for (int ai = 0; ai < 2; ++ai)
; #pragma unroll
;             for (int m = 0; m < 4; ++m) { const int row = row0 + ai * HALF + m * 16;
; #pragma unroll
;                 for (int bj = 0; bj < 2; ++bj) { const int col = col0 + bj * HALF;
;                     float gf[8], r[8]; unpack8(*(const u32x4*)(gr + (size_t)row * NPROJ + col), gf);
;                     const f32x4 v0 = acc[ai][bj][m][0], v1 = acc[ai][bj][m][1];
; #pragma unroll
;                     for (int j = 0; j < 4; ++j) { r[j] = v0[j] * sigmoidf_(gf[j]); r[4 + j] = v1[j] * sigmoidf_(gf[4 + j]); }
;                     *(u32x4*)(O + (size_t)row * D + col) = pack8(r); } }
;     }
	s_nop 0
	v_mov_b64_e32 v[72:73], v[218:219]
	v_mov_b64_e32 v[74:75], v[220:221]
	v_lshlrev_b64 v[68:69], 11, v[156:157]
	v_lshlrev_b32_e32 v0, 16, v72
	v_mul_f32_e32 v0, 0xbfb8aa3b, v0
	v_exp_f32_e32 v0, v0
	v_lshlrev_b32_e32 v77, 16, v73
	v_and_b32_e32 v78, 0xffff0000, v73
	v_lshlrev_b32_e32 v73, 16, v74
	v_add_f32_e32 v0, 1.0, v0
	v_and_b32_e32 v76, 0xffff0000, v72
	v_rcp_f32_e32 v72, v0
	v_mul_f32_e32 v0, 0xbfb8aa3b, v73
	v_exp_f32_e32 v0, v0
	v_and_b32_e32 v79, 0xffff0000, v74
	v_lshlrev_b32_e32 v80, 16, v75
	v_and_b32_e32 v81, 0xffff0000, v75
	v_add_f32_e32 v0, 1.0, v0
	v_rcp_f32_e32 v74, v0
	v_mul_f32_e32 v0, 0xbfb8aa3b, v76
	v_exp_f32_e32 v0, v0
	s_nop 0
	v_add_f32_e32 v0, 1.0, v0
	v_rcp_f32_e32 v73, v0
	v_mul_f32_e32 v0, 0xbfb8aa3b, v79
	v_exp_f32_e32 v0, v0
	v_pk_mul_f32 v[64:65], v[64:65], v[72:73]
	v_add_f32_e32 v0, 1.0, v0
	v_rcp_f32_e32 v75, v0
	v_mul_f32_e32 v0, 0xbfb8aa3b, v77
	v_exp_f32_e32 v0, v0
	v_pk_mul_f32 v[72:73], v[60:61], v[74:75]
	v_add_f32_e32 v0, 1.0, v0
	v_rcp_f32_e32 v60, v0
	v_mul_f32_e32 v0, 0xbfb8aa3b, v80
	v_exp_f32_e32 v0, v0
	s_nop 0
	v_add_f32_e32 v0, 1.0, v0
	v_rcp_f32_e32 v74, v0
	v_mul_f32_e32 v0, 0xbfb8aa3b, v78
	v_exp_f32_e32 v0, v0
	s_nop 0
	v_add_f32_e32 v0, 1.0, v0
	v_rcp_f32_e32 v61, v0
	v_mul_f32_e32 v0, 0xbfb8aa3b, v81
	v_exp_f32_e32 v0, v0
	v_pk_mul_f32 v[66:67], v[66:67], v[60:61]
	v_cvt_pk_bf16_f32 v60, v64, v65
	v_add_f32_e32 v0, 1.0, v0
	v_rcp_f32_e32 v75, v0
	v_lshl_add_u64 v[64:65], s[94:95], 0, v[68:69]
	v_cvt_pk_bf16_f32 v61, v66, v67
	v_lshl_add_u64 v[64:65], v[64:65], 0, v[2:3]
	v_pk_mul_f32 v[74:75], v[62:63], v[74:75]
	v_cvt_pk_bf16_f32 v62, v72, v73
	v_cvt_pk_bf16_f32 v63, v74, v75
	global_store_dwordx4 v[64:65], v[60:63], off
	s_waitcnt vmcnt(6)
	s_nop 0
	v_mov_b64_e32 v[60:61], v[222:223]
	v_mov_b64_e32 v[62:63], v[224:225]
	v_lshlrev_b32_e32 v0, 16, v60
	v_mul_f32_e32 v0, 0xbfb8aa3b, v0
	v_exp_f32_e32 v0, v0
	v_lshlrev_b32_e32 v67, 16, v61
	v_and_b32_e32 v68, 0xffff0000, v61
	v_lshlrev_b32_e32 v61, 16, v62
	v_add_f32_e32 v0, 1.0, v0
	v_and_b32_e32 v66, 0xffff0000, v60
	v_rcp_f32_e32 v60, v0
	v_mul_f32_e32 v0, 0xbfb8aa3b, v61
	v_exp_f32_e32 v0, v0
	v_and_b32_e32 v69, 0xffff0000, v62
	v_lshlrev_b32_e32 v70, 16, v63
	v_and_b32_e32 v71, 0xffff0000, v63
	v_add_f32_e32 v0, 1.0, v0
	v_rcp_f32_e32 v62, v0
	v_mul_f32_e32 v0, 0xbfb8aa3b, v66
	v_exp_f32_e32 v0, v0
	s_nop 0
	v_add_f32_e32 v0, 1.0, v0
	v_rcp_f32_e32 v61, v0
	v_mul_f32_e32 v0, 0xbfb8aa3b, v69
	v_exp_f32_e32 v0, v0
	v_pk_mul_f32 v[56:57], v[56:57], v[60:61]
	v_add_f32_e32 v0, 1.0, v0
	v_rcp_f32_e32 v63, v0
	v_mul_f32_e32 v0, 0xbfb8aa3b, v67
	v_exp_f32_e32 v0, v0
	v_pk_mul_f32 v[60:61], v[52:53], v[62:63]
	v_add_f32_e32 v0, 1.0, v0
	v_rcp_f32_e32 v52, v0
	v_mul_f32_e32 v0, 0xbfb8aa3b, v70
	v_exp_f32_e32 v0, v0
	s_nop 0
	v_add_f32_e32 v0, 1.0, v0
	v_rcp_f32_e32 v62, v0
	v_mul_f32_e32 v0, 0xbfb8aa3b, v68
	v_exp_f32_e32 v0, v0
	s_nop 0
	v_add_f32_e32 v0, 1.0, v0
	v_rcp_f32_e32 v53, v0
	v_mul_f32_e32 v0, 0xbfb8aa3b, v71
	v_exp_f32_e32 v0, v0
	v_pk_mul_f32 v[58:59], v[58:59], v[52:53]
	v_cvt_pk_bf16_f32 v52, v56, v57
	v_add_f32_e32 v0, 1.0, v0
	v_rcp_f32_e32 v63, v0
	v_cvt_pk_bf16_f32 v53, v58, v59
	v_pk_mul_f32 v[62:63], v[54:55], v[62:63]
	v_cvt_pk_bf16_f32 v54, v60, v61
	v_cvt_pk_bf16_f32 v55, v62, v63
	global_store_dwordx4 v[64:65], v[52:55], off offset:256
	s_nop 1
	v_mad_i64_i32 v[54:55], s[10:11], v154, s18, v[132:133]
	v_lshl_add_u64 v[54:55], v[54:55], 0, v[2:3]
	s_waitcnt vmcnt(5)
	s_nop 0
	v_mov_b64_e32 v[56:57], v[226:227]
	v_mov_b64_e32 v[58:59], v[228:229]
	v_lshlrev_b64 v[52:53], 11, v[154:155]
	v_lshlrev_b32_e32 v0, 16, v56
	v_mul_f32_e32 v0, 0xbfb8aa3b, v0
	v_exp_f32_e32 v0, v0
	v_lshlrev_b32_e32 v61, 16, v57
	v_and_b32_e32 v62, 0xffff0000, v57
	v_lshlrev_b32_e32 v57, 16, v58
	v_add_f32_e32 v0, 1.0, v0
	v_and_b32_e32 v60, 0xffff0000, v56
	v_rcp_f32_e32 v56, v0
	v_mul_f32_e32 v0, 0xbfb8aa3b, v57
	v_exp_f32_e32 v0, v0
	v_and_b32_e32 v63, 0xffff0000, v58
	v_lshlrev_b32_e32 v64, 16, v59
	v_and_b32_e32 v65, 0xffff0000, v59
	v_add_f32_e32 v0, 1.0, v0
	v_rcp_f32_e32 v58, v0
	v_mul_f32_e32 v0, 0xbfb8aa3b, v60
	v_exp_f32_e32 v0, v0
	s_nop 0
	v_add_f32_e32 v0, 1.0, v0
	v_rcp_f32_e32 v57, v0
	v_mul_f32_e32 v0, 0xbfb8aa3b, v63
	v_exp_f32_e32 v0, v0
	v_pk_mul_f32 v[48:49], v[48:49], v[56:57]
	v_add_f32_e32 v0, 1.0, v0
	v_rcp_f32_e32 v59, v0
	v_mul_f32_e32 v0, 0xbfb8aa3b, v61
	v_exp_f32_e32 v0, v0
	v_pk_mul_f32 v[56:57], v[44:45], v[58:59]
	v_add_f32_e32 v0, 1.0, v0
	v_rcp_f32_e32 v44, v0
	v_mul_f32_e32 v0, 0xbfb8aa3b, v64
	v_exp_f32_e32 v0, v0
	s_nop 0
	v_add_f32_e32 v0, 1.0, v0
	v_rcp_f32_e32 v58, v0
	v_mul_f32_e32 v0, 0xbfb8aa3b, v62
	v_exp_f32_e32 v0, v0
	s_nop 0
	v_add_f32_e32 v0, 1.0, v0
	v_rcp_f32_e32 v45, v0
	v_mul_f32_e32 v0, 0xbfb8aa3b, v65
	v_exp_f32_e32 v0, v0
	v_pk_mul_f32 v[50:51], v[50:51], v[44:45]
	v_cvt_pk_bf16_f32 v44, v48, v49
	v_add_f32_e32 v0, 1.0, v0
	v_rcp_f32_e32 v59, v0
	v_lshl_add_u64 v[48:49], s[94:95], 0, v[52:53]
	v_cvt_pk_bf16_f32 v45, v50, v51
	v_lshl_add_u64 v[48:49], v[48:49], 0, v[2:3]
	v_pk_mul_f32 v[58:59], v[46:47], v[58:59]
	v_cvt_pk_bf16_f32 v46, v56, v57
	v_cvt_pk_bf16_f32 v47, v58, v59
	global_store_dwordx4 v[48:49], v[44:47], off
	s_waitcnt vmcnt(4)
; __device__ __forceinline__ float sigmoidf_(float x) { return __builtin_amdgcn_rcpf(1.0f + __expf(-x)); }
; __device__ __forceinline__ void unpack8(const u32x4 w, float* f) { f[0] = bf_lo(w.x); f[1] = bf_hi(w.x); f[2] = bf_lo(w.y); f[3] = bf_hi(w.y); f[4] = bf_lo(w.z); f[5] = bf_hi(w.z); f[6] = bf_lo(w.w); f[7] = bf_hi(w.w); }
; __device__ __forceinline__ u32x4 pack8(const float* f) { u32x4 w; w.x = cvt_pk_bf16(f[0], f[1]); w.y = cvt_pk_bf16(f[2], f[3]); w.z = cvt_pk_bf16(f[4], f[5]); w.w = cvt_pk_bf16(f[6], f[7]); return w; }
;     __device__ __forceinline__ void operator()(const f32x4 (&acc)[2][2][4][2], const Unit& u, int wr, int wc, int fr, int fq) const { if (u.kind == 0) e0(acc, u, wr, wc, fr, fq); else e1(acc, u, wr, wc, fr, fq); }
;     __device__ __forceinline__ void operator()(const f32x4 (&acc)[2][2][4][2], const Unit& u, int wr, int wc, int fr, int fq) const {
;         const int row0 = u.pm * BM + wr * 64 + fr, col0 = u.pn * BM + wc * 32 + 8 * fq;
; #pragma unroll
;         for (int ai = 0; ai < 2; ++ai)
; #pragma unroll
;             for (int m = 0; m < 4; ++m) { const int row = row0 + ai * HALF + m * 16;
; #pragma unroll
;                 for (int bj = 0; bj < 2; ++bj) { const int col = col0 + bj * HALF;
;                     float gf[8], r[8]; unpack8(*(const u32x4*)(gr + (size_t)row * NPROJ + col), gf);
;                     const f32x4 v0 = acc[ai][bj][m][0], v1 = acc[ai][bj][m][1];
; #pragma unroll
;                     for (int j = 0; j < 4; ++j) { r[j] = v0[j] * sigmoidf_(gf[j]); r[4 + j] = v1[j] * sigmoidf_(gf[4 + j]); }
;                     *(u32x4*)(O + (size_t)row * D + col) = pack8(r); } }
;     }
	s_nop 0
	v_mov_b64_e32 v[44:45], v[236:237]
	v_mov_b64_e32 v[46:47], v[238:239]
	v_lshlrev_b32_e32 v0, 16, v44
	v_mul_f32_e32 v0, 0xbfb8aa3b, v0
	v_exp_f32_e32 v0, v0
	v_lshlrev_b32_e32 v51, 16, v45
	v_and_b32_e32 v52, 0xffff0000, v45
	v_lshlrev_b32_e32 v45, 16, v46
	v_add_f32_e32 v0, 1.0, v0
	v_and_b32_e32 v50, 0xffff0000, v44
	v_rcp_f32_e32 v44, v0
	v_mul_f32_e32 v0, 0xbfb8aa3b, v45
	v_exp_f32_e32 v0, v0
	v_and_b32_e32 v53, 0xffff0000, v46
	v_lshlrev_b32_e32 v54, 16, v47
	v_and_b32_e32 v55, 0xffff0000, v47
	v_add_f32_e32 v0, 1.0, v0
	v_rcp_f32_e32 v46, v0
	v_mul_f32_e32 v0, 0xbfb8aa3b, v50
	v_exp_f32_e32 v0, v0
	s_nop 0
	v_add_f32_e32 v0, 1.0, v0
	v_rcp_f32_e32 v45, v0
	v_mul_f32_e32 v0, 0xbfb8aa3b, v53
	v_exp_f32_e32 v0, v0
	v_pk_mul_f32 v[40:41], v[40:41], v[44:45]
	v_add_f32_e32 v0, 1.0, v0
	v_rcp_f32_e32 v47, v0
	v_mul_f32_e32 v0, 0xbfb8aa3b, v51
	v_exp_f32_e32 v0, v0
	v_pk_mul_f32 v[44:45], v[36:37], v[46:47]
	v_add_f32_e32 v0, 1.0, v0
	v_rcp_f32_e32 v36, v0
	v_mul_f32_e32 v0, 0xbfb8aa3b, v54
	v_exp_f32_e32 v0, v0
	s_nop 0
	v_add_f32_e32 v0, 1.0, v0
	v_rcp_f32_e32 v46, v0
	v_mul_f32_e32 v0, 0xbfb8aa3b, v52
	v_exp_f32_e32 v0, v0
	s_nop 0
	v_add_f32_e32 v0, 1.0, v0
	v_rcp_f32_e32 v37, v0
	v_mul_f32_e32 v0, 0xbfb8aa3b, v55
	v_exp_f32_e32 v0, v0
	v_pk_mul_f32 v[42:43], v[42:43], v[36:37]
	v_cvt_pk_bf16_f32 v36, v40, v41
	v_add_f32_e32 v0, 1.0, v0
	v_rcp_f32_e32 v47, v0
	v_cvt_pk_bf16_f32 v37, v42, v43
	v_pk_mul_f32 v[46:47], v[38:39], v[46:47]
	v_cvt_pk_bf16_f32 v38, v44, v45
	v_cvt_pk_bf16_f32 v39, v46, v47
	global_store_dwordx4 v[48:49], v[36:39], off offset:256
	s_nop 1
	v_mad_i64_i32 v[38:39], s[10:11], v152, s18, v[132:133]
	v_lshl_add_u64 v[38:39], v[38:39], 0, v[2:3]
	s_waitcnt vmcnt(3)
	s_nop 0
	v_mov_b64_e32 v[40:41], v[168:169]
	v_mov_b64_e32 v[42:43], v[170:171]
	v_lshlrev_b64 v[36:37], 11, v[152:153]
	v_lshlrev_b32_e32 v0, 16, v40
	v_mul_f32_e32 v0, 0xbfb8aa3b, v0
	v_exp_f32_e32 v0, v0
	v_lshlrev_b32_e32 v45, 16, v41
	v_and_b32_e32 v46, 0xffff0000, v41
	v_lshlrev_b32_e32 v41, 16, v42
	v_add_f32_e32 v0, 1.0, v0
	v_and_b32_e32 v44, 0xffff0000, v40
	v_rcp_f32_e32 v40, v0
	v_mul_f32_e32 v0, 0xbfb8aa3b, v41
	v_exp_f32_e32 v0, v0
	v_and_b32_e32 v47, 0xffff0000, v42
	v_lshlrev_b32_e32 v48, 16, v43
	v_and_b32_e32 v49, 0xffff0000, v43
	v_add_f32_e32 v0, 1.0, v0
	v_rcp_f32_e32 v42, v0
	v_mul_f32_e32 v0, 0xbfb8aa3b, v44
	v_exp_f32_e32 v0, v0
	s_nop 0
	v_add_f32_e32 v0, 1.0, v0
	v_rcp_f32_e32 v41, v0
	v_mul_f32_e32 v0, 0xbfb8aa3b, v47
	v_exp_f32_e32 v0, v0
	v_pk_mul_f32 v[32:33], v[32:33], v[40:41]
	v_add_f32_e32 v0, 1.0, v0
	v_rcp_f32_e32 v43, v0
	v_mul_f32_e32 v0, 0xbfb8aa3b, v45
	v_exp_f32_e32 v0, v0
	v_pk_mul_f32 v[40:41], v[28:29], v[42:43]
	v_add_f32_e32 v0, 1.0, v0
	v_rcp_f32_e32 v28, v0
	v_mul_f32_e32 v0, 0xbfb8aa3b, v48
	v_exp_f32_e32 v0, v0
	s_nop 0
	v_add_f32_e32 v0, 1.0, v0
	v_rcp_f32_e32 v42, v0
	v_mul_f32_e32 v0, 0xbfb8aa3b, v46
	v_exp_f32_e32 v0, v0
	s_nop 0
	v_add_f32_e32 v0, 1.0, v0
	v_rcp_f32_e32 v29, v0
	v_mul_f32_e32 v0, 0xbfb8aa3b, v49
	v_exp_f32_e32 v0, v0
	v_pk_mul_f32 v[34:35], v[34:35], v[28:29]
	v_cvt_pk_bf16_f32 v28, v32, v33
	v_add_f32_e32 v0, 1.0, v0
	v_rcp_f32_e32 v43, v0
	v_lshl_add_u64 v[32:33], s[94:95], 0, v[36:37]
	v_cvt_pk_bf16_f32 v29, v34, v35
	v_lshl_add_u64 v[32:33], v[32:33], 0, v[2:3]
	v_pk_mul_f32 v[42:43], v[30:31], v[42:43]
	v_cvt_pk_bf16_f32 v30, v40, v41
	v_cvt_pk_bf16_f32 v31, v42, v43
	global_store_dwordx4 v[32:33], v[28:31], off
	s_waitcnt vmcnt(2)
; __device__ __forceinline__ float sigmoidf_(float x) { return __builtin_amdgcn_rcpf(1.0f + __expf(-x)); }
; __device__ __forceinline__ void unpack8(const u32x4 w, float* f) { f[0] = bf_lo(w.x); f[1] = bf_hi(w.x); f[2] = bf_lo(w.y); f[3] = bf_hi(w.y); f[4] = bf_lo(w.z); f[5] = bf_hi(w.z); f[6] = bf_lo(w.w); f[7] = bf_hi(w.w); }
; __device__ __forceinline__ u32x4 pack8(const float* f) { u32x4 w; w.x = cvt_pk_bf16(f[0], f[1]); w.y = cvt_pk_bf16(f[2], f[3]); w.z = cvt_pk_bf16(f[4], f[5]); w.w = cvt_pk_bf16(f[6], f[7]); return w; }
;     __device__ __forceinline__ void operator()(const f32x4 (&acc)[2][2][4][2], const Unit& u, int wr, int wc, int fr, int fq) const { if (u.kind == 0) e0(acc, u, wr, wc, fr, fq); else e1(acc, u, wr, wc, fr, fq); }
;     __device__ __forceinline__ void operator()(const f32x4 (&acc)[2][2][4][2], const Unit& u, int wr, int wc, int fr, int fq) const {
;         const int row0 = u.pm * BM + wr * 64 + fr, col0 = u.pn * BM + wc * 32 + 8 * fq;
; #pragma unroll
;         for (int ai = 0; ai < 2; ++ai)
; #pragma unroll
;             for (int m = 0; m < 4; ++m) { const int row = row0 + ai * HALF + m * 16;
; #pragma unroll
;                 for (int bj = 0; bj < 2; ++bj) { const int col = col0 + bj * HALF;
;                     float gf[8], r[8]; unpack8(*(const u32x4*)(gr + (size_t)row * NPROJ + col), gf);
;                     const f32x4 v0 = acc[ai][bj][m][0], v1 = acc[ai][bj][m][1];
; #pragma unroll
;                     for (int j = 0; j < 4; ++j) { r[j] = v0[j] * sigmoidf_(gf[j]); r[4 + j] = v1[j] * sigmoidf_(gf[4 + j]); }
;                     *(u32x4*)(O + (size_t)row * D + col) = pack8(r); } }
;     }
	s_nop 0
	v_mov_b64_e32 v[28:29], v[190:191]
	v_mov_b64_e32 v[30:31], v[192:193]
	v_lshlrev_b32_e32 v0, 16, v28
	v_mul_f32_e32 v0, 0xbfb8aa3b, v0
	v_exp_f32_e32 v0, v0
	v_lshlrev_b32_e32 v35, 16, v29
	v_and_b32_e32 v36, 0xffff0000, v29
	v_lshlrev_b32_e32 v29, 16, v30
	v_add_f32_e32 v0, 1.0, v0
	v_and_b32_e32 v34, 0xffff0000, v28
	v_rcp_f32_e32 v28, v0
	v_mul_f32_e32 v0, 0xbfb8aa3b, v29
	v_exp_f32_e32 v0, v0
	v_and_b32_e32 v37, 0xffff0000, v30
	v_lshlrev_b32_e32 v38, 16, v31
	v_and_b32_e32 v39, 0xffff0000, v31
	v_add_f32_e32 v0, 1.0, v0
	v_rcp_f32_e32 v30, v0
	v_mul_f32_e32 v0, 0xbfb8aa3b, v34
	v_exp_f32_e32 v0, v0
	s_nop 0
	v_add_f32_e32 v0, 1.0, v0
	v_rcp_f32_e32 v29, v0
	v_mul_f32_e32 v0, 0xbfb8aa3b, v37
	v_exp_f32_e32 v0, v0
	v_pk_mul_f32 v[24:25], v[24:25], v[28:29]
	v_add_f32_e32 v0, 1.0, v0
	v_rcp_f32_e32 v31, v0
	v_mul_f32_e32 v0, 0xbfb8aa3b, v35
	v_exp_f32_e32 v0, v0
	v_pk_mul_f32 v[28:29], v[20:21], v[30:31]
	v_add_f32_e32 v0, 1.0, v0
	v_rcp_f32_e32 v20, v0
	v_mul_f32_e32 v0, 0xbfb8aa3b, v38
	v_exp_f32_e32 v0, v0
	s_nop 0
	v_add_f32_e32 v0, 1.0, v0
	v_rcp_f32_e32 v30, v0
	v_mul_f32_e32 v0, 0xbfb8aa3b, v36
	v_exp_f32_e32 v0, v0
	s_nop 0
	v_add_f32_e32 v0, 1.0, v0
	v_rcp_f32_e32 v21, v0
	v_mul_f32_e32 v0, 0xbfb8aa3b, v39
	v_exp_f32_e32 v0, v0
	v_pk_mul_f32 v[26:27], v[26:27], v[20:21]
	v_cvt_pk_bf16_f32 v20, v24, v25
	v_add_f32_e32 v0, 1.0, v0
	v_rcp_f32_e32 v31, v0
	v_cvt_pk_bf16_f32 v21, v26, v27
	v_pk_mul_f32 v[30:31], v[22:23], v[30:31]
	v_cvt_pk_bf16_f32 v22, v28, v29
	v_cvt_pk_bf16_f32 v23, v30, v31
	global_store_dwordx4 v[32:33], v[20:23], off offset:256
	s_nop 1
	v_mad_i64_i32 v[22:23], s[10:11], v150, s18, v[132:133]
	v_lshl_add_u64 v[22:23], v[22:23], 0, v[2:3]
	s_waitcnt vmcnt(1)
	s_nop 0
	v_mov_b64_e32 v[24:25], v[194:195]
	v_mov_b64_e32 v[26:27], v[196:197]
	v_lshlrev_b64 v[20:21], 11, v[150:151]
	s_mov_b32 s10, s93
	s_mov_b32 s11, s72
	v_lshlrev_b32_e32 v0, 16, v24
	v_mul_f32_e32 v0, 0xbfb8aa3b, v0
	v_exp_f32_e32 v0, v0
	v_lshlrev_b32_e32 v29, 16, v25
	v_and_b32_e32 v30, 0xffff0000, v25
	v_lshlrev_b32_e32 v25, 16, v26
	v_add_f32_e32 v0, 1.0, v0
	v_and_b32_e32 v28, 0xffff0000, v24
	v_rcp_f32_e32 v24, v0
	v_mul_f32_e32 v0, 0xbfb8aa3b, v25
	v_exp_f32_e32 v0, v0
	v_and_b32_e32 v31, 0xffff0000, v26
	v_lshlrev_b32_e32 v32, 16, v27
	v_and_b32_e32 v33, 0xffff0000, v27
	v_add_f32_e32 v0, 1.0, v0
	v_rcp_f32_e32 v26, v0
	v_mul_f32_e32 v0, 0xbfb8aa3b, v28
	v_exp_f32_e32 v0, v0
	s_nop 0
	v_add_f32_e32 v0, 1.0, v0
	v_rcp_f32_e32 v25, v0
	v_mul_f32_e32 v0, 0xbfb8aa3b, v31
	v_exp_f32_e32 v0, v0
	v_pk_mul_f32 v[16:17], v[16:17], v[24:25]
	v_add_f32_e32 v0, 1.0, v0
	v_rcp_f32_e32 v27, v0
	v_mul_f32_e32 v0, 0xbfb8aa3b, v29
	v_exp_f32_e32 v0, v0
	v_pk_mul_f32 v[24:25], v[12:13], v[26:27]
	v_add_f32_e32 v0, 1.0, v0
	v_rcp_f32_e32 v12, v0
	v_mul_f32_e32 v0, 0xbfb8aa3b, v32
	v_exp_f32_e32 v0, v0
	s_nop 0
	v_add_f32_e32 v0, 1.0, v0
	v_rcp_f32_e32 v26, v0
	v_mul_f32_e32 v0, 0xbfb8aa3b, v30
	v_exp_f32_e32 v0, v0
	s_nop 0
	v_add_f32_e32 v0, 1.0, v0
	v_rcp_f32_e32 v13, v0
	v_mul_f32_e32 v0, 0xbfb8aa3b, v33
	v_exp_f32_e32 v0, v0
	v_pk_mul_f32 v[18:19], v[18:19], v[12:13]
	v_cvt_pk_bf16_f32 v12, v16, v17
	v_add_f32_e32 v0, 1.0, v0
	v_rcp_f32_e32 v27, v0
	v_lshl_add_u64 v[16:17], s[94:95], 0, v[20:21]
	v_cvt_pk_bf16_f32 v13, v18, v19
	v_lshl_add_u64 v[16:17], v[16:17], 0, v[2:3]
	v_pk_mul_f32 v[26:27], v[14:15], v[26:27]
	v_cvt_pk_bf16_f32 v14, v24, v25
	v_cvt_pk_bf16_f32 v15, v26, v27
	global_store_dwordx4 v[16:17], v[12:15], off
	s_waitcnt vmcnt(0)
	s_nop 0
	v_mov_b64_e32 v[12:13], v[198:199]
	v_mov_b64_e32 v[14:15], v[200:201]
	v_lshlrev_b32_e32 v0, 16, v12
	v_mul_f32_e32 v0, 0xbfb8aa3b, v0
	v_exp_f32_e32 v0, v0
	v_and_b32_e32 v3, 0xffff0000, v12
	v_lshlrev_b32_e32 v12, 16, v14
	v_lshlrev_b32_e32 v18, 16, v13
	v_add_f32_e32 v0, 1.0, v0
	v_rcp_f32_e32 v2, v0
	v_mul_f32_e32 v0, 0xbfb8aa3b, v12
	v_exp_f32_e32 v0, v0
	v_and_b32_e32 v19, 0xffff0000, v13
	v_and_b32_e32 v13, 0xffff0000, v14
	v_lshlrev_b32_e32 v14, 16, v15
	v_add_f32_e32 v0, 1.0, v0
	v_rcp_f32_e32 v12, v0
	v_mul_f32_e32 v0, 0xbfb8aa3b, v3
	v_exp_f32_e32 v0, v0
	v_and_b32_e32 v15, 0xffff0000, v15
	v_add_f32_e32 v0, 1.0, v0
	v_rcp_f32_e32 v3, v0
	v_mul_f32_e32 v0, 0xbfb8aa3b, v13
	v_exp_f32_e32 v0, v0
	v_pk_mul_f32 v[2:3], v[8:9], v[2:3]
	s_nop 0
	v_cvt_pk_bf16_f32 v2, v2, v3
	v_add_f32_e32 v0, 1.0, v0
	v_rcp_f32_e32 v13, v0
	v_mul_f32_e32 v0, 0xbfb8aa3b, v18
	v_exp_f32_e32 v0, v0
	v_pk_mul_f32 v[4:5], v[4:5], v[12:13]
	s_nop 0
	v_cvt_pk_bf16_f32 v4, v4, v5
	v_add_f32_e32 v0, 1.0, v0
	v_rcp_f32_e32 v8, v0
	v_mul_f32_e32 v0, 0xbfb8aa3b, v14
	v_exp_f32_e32 v0, v0
	s_nop 0
	v_add_f32_e32 v0, 1.0, v0
	v_rcp_f32_e32 v12, v0
	v_mul_f32_e32 v0, 0xbfb8aa3b, v19
	v_exp_f32_e32 v0, v0
	s_nop 0
	v_add_f32_e32 v0, 1.0, v0
	v_rcp_f32_e32 v9, v0
	v_mul_f32_e32 v0, 0xbfb8aa3b, v15
	v_exp_f32_e32 v0, v0
	v_pk_mul_f32 v[8:9], v[10:11], v[8:9]
	s_nop 0
	v_cvt_pk_bf16_f32 v3, v8, v9
	v_add_f32_e32 v0, 1.0, v0
	v_rcp_f32_e32 v13, v0
	s_nop 0
	v_pk_mul_f32 v[6:7], v[6:7], v[12:13]
	s_nop 0
	v_cvt_pk_bf16_f32 v5, v6, v7
	global_store_dwordx4 v[16:17], v[2:5], off offset:256
	s_cbranch_vccnz .LBB0_563

; __device__ __forceinline__ void unpack8(const u32x4 w, float* f) { f[0] = bf_lo(w.x); f[1] = bf_hi(w.x); f[2] = bf_lo(w.y); f[3] = bf_hi(w.y); f[4] = bf_lo(w.z); f[5] = bf_hi(w.z); f[6] = bf_lo(w.w); f[7] = bf_hi(w.w); }
; __device__ __forceinline__ int otid() { int t = threadIdx.x; asm volatile("" : "+v"(t)); return t; }
; __device__ __forceinline__ int ogrid() { int g = gridDim.x; asm volatile("" : "+s"(g)); return g; }
; __device__ __forceinline__ float sum16(const float* p) { const f32x4 a = *(const f32x4*)p, b = *(const f32x4*)(p + 4), c = *(const f32x4*)(p + 8), d = *(const f32x4*)(p + 12); const f32x4 t = (a + b) + (c + d); return (t[0] + t[1]) + (t[2] + t[3]); }
; __device__ __forceinline__ void phase_final(const bf16_t* __restrict__ xb, float* xo, const float* rowss1, const float* __restrict__ gfin) {
;     const int tid = otid(), lane = tid & 63, nw = ogrid() * 8;
;     for (int row = blockIdx.x * 8 + (tid >> 6); row < MG; row += nw) {
;         const float rs = rsqrtf(sum16(rowss1 + (size_t)row * 16) * (1.0f / 1024.0f) + EPS);
; #pragma unroll
;         for (int i = 0; i < 2; ++i) { const int c8 = (lane + 64 * i) * 8; float x[8]; unpack8(__builtin_nontemporal_load((const u32x4*)(xb + (size_t)row * D + c8)), x);
;             const f32x4 g0 = *(const f32x4*)(gfin + c8), g1 = *(const f32x4*)(gfin + c8 + 4);
;             __builtin_nontemporal_store((f32x4){x[0] * rs * g0[0], x[1] * rs * g0[1], x[2] * rs * g0[2], x[3] * rs * g0[3]}, (f32x4*)(xo + (size_t)row * D + c8));
;             __builtin_nontemporal_store((f32x4){x[4] * rs * g1[0], x[5] * rs * g1[1], x[6] * rs * g1[2], x[7] * rs * g1[3]}, (f32x4*)(xo + (size_t)row * D + c8 + 4)); }
;     }
.LBB0_926:
	global_load_dwordx4 v[26:29], v[20:21], off offset:32
	global_load_dwordx4 v[30:33], v[20:21], off offset:48
	global_load_dwordx4 v[34:37], v[20:21], off
	global_load_dwordx4 v[38:41], v[20:21], off offset:16
	global_load_dwordx4 v[42:45], v[22:23], off nt
	global_load_dwordx4 v[46:49], v[22:23], off offset:1024 nt
	v_add_u32_e32 v18, s8, v18
	v_lshl_add_u64 v[20:21], v[20:21], 0, s[28:29]
	s_waitcnt vmcnt(4)
	v_pk_add_f32 v[28:29], v[28:29], v[32:33]
	v_pk_add_f32 v[26:27], v[26:27], v[30:31]
	s_waitcnt vmcnt(2)
	v_pk_add_f32 v[36:37], v[36:37], v[40:41]
	v_pk_add_f32 v[34:35], v[34:35], v[38:39]
	v_pk_add_f32 v[28:29], v[36:37], v[28:29]
	v_pk_add_f32 v[26:27], v[34:35], v[26:27]
	s_nop 0
	v_pk_mov_b32 v[30:31], v[26:27], v[28:29] op_sel:[1,0]
	v_mov_b32_e32 v27, v29
	v_pk_add_f32 v[26:27], v[30:31], v[26:27]
	s_nop 0
	v_add_f32_e32 v0, v26, v27
	s_waitcnt vmcnt(0)
	v_mov_b64_e32 v[26:27], v[42:43]
	v_mov_b64_e32 v[28:29], v[44:45]
	v_fmamk_f32 v0, v0, 0x3a800000, v234
	v_cmp_gt_f32_e32 vcc, s65, v0
	v_mul_f32_e32 v19, 0x4b800000, v0
	v_lshlrev_b32_e32 v30, 16, v26
	v_cndmask_b32_e32 v0, v0, v19, vcc
	v_rsq_f32_e32 v0, v0
	v_and_b32_e32 v31, 0xffff0000, v26
	v_lshlrev_b32_e32 v26, 16, v27
	v_and_b32_e32 v27, 0xffff0000, v27
	v_mul_f32_e32 v19, 0x45800000, v0
	v_cndmask_b32_e32 v0, v0, v19, vcc
	v_pk_mul_f32 v[26:27], v[0:1], v[26:27] op_sel_hi:[0,1]
	v_pk_mul_f32 v[32:33], v[8:9], v[26:27]
	v_lshlrev_b32_e32 v26, 16, v28
	v_and_b32_e32 v27, 0xffff0000, v28
	v_lshlrev_b32_e32 v28, 16, v29
	v_and_b32_e32 v29, 0xffff0000, v29
	v_pk_mul_f32 v[26:27], v[0:1], v[26:27] op_sel_hi:[0,1]
	v_pk_mul_f32 v[28:29], v[0:1], v[28:29] op_sel_hi:[0,1]
	v_pk_mul_f32 v[26:27], v[2:3], v[26:27]
	v_pk_mul_f32 v[28:29], v[4:5], v[28:29]
	global_store_dwordx4 v[24:25], v[26:29], off offset:-2048 nt
	v_pk_mul_f32 v[30:31], v[0:1], v[30:31] op_sel_hi:[0,1]
	v_pk_mul_f32 v[30:31], v[6:7], v[30:31]
	global_store_dwordx4 v[24:25], v[30:33], off offset:-2064 nt
	v_mov_b64_e32 v[26:27], v[46:47]
	v_mov_b64_e32 v[28:29], v[48:49]
	v_cmp_lt_i32_e32 vcc, s11, v18
	v_lshl_add_u64 v[22:23], v[22:23], 0, s[40:41]
	s_or_b64 s[44:45], vcc, s[44:45]
	v_lshlrev_b32_e32 v30, 16, v26
	v_and_b32_e32 v31, 0xffff0000, v26
	v_lshlrev_b32_e32 v26, 16, v27
	v_and_b32_e32 v27, 0xffff0000, v27
	v_pk_mul_f32 v[26:27], v[0:1], v[26:27] op_sel_hi:[0,1]
	v_pk_mul_f32 v[32:33], v[16:17], v[26:27]
	v_lshlrev_b32_e32 v26, 16, v28
	v_and_b32_e32 v27, 0xffff0000, v28
	v_lshlrev_b32_e32 v28, 16, v29
	v_and_b32_e32 v29, 0xffff0000, v29
	v_pk_mul_f32 v[30:31], v[0:1], v[30:31] op_sel_hi:[0,1]
	v_pk_mul_f32 v[26:27], v[0:1], v[26:27] op_sel_hi:[0,1]
	v_pk_mul_f32 v[28:29], v[0:1], v[28:29] op_sel_hi:[0,1]
	v_pk_mul_f32 v[30:31], v[14:15], v[30:31]
	v_pk_mul_f32 v[26:27], v[10:11], v[26:27]
	v_pk_mul_f32 v[28:29], v[12:13], v[28:29]
	global_store_dwordx4 v[24:25], v[30:33], off offset:-16 nt
	global_store_dwordx4 v[24:25], v[26:29], off nt
	v_lshl_add_u64 v[24:25], v[24:25], 0, s[42:43]
	s_andn2_b64 exec, exec, s[44:45]
	s_cbranch_execnz .LBB0_926
	s_branch .LBB0_923
